# G2 gate tail GEMM: its two-chain K-split reduction de-serialised too (16 ds_reads together, counted lgkmcnt waits)
# baseline (speedup 1.0000x reference)
.LBB0_772:
	s_and_b32 s20, s16, 0x70
	v_or_b32_e32 v2, s20, v22
	s_movk_i32 s22, 0xc00
	v_mad_u64_u32 v[92:93], s[20:21], v2, s22, v[0:1]
	s_and_b32 s20, s17, 0xffffffc0
	s_nop 0
	v_or_b32_e32 v6, s20, v18
	v_mad_i64_i32 v[116:117], s[22:23], v6, s22, v[4:5]
	v_lshl_add_u64 v[64:65], v[116:117], 0, s[10:11]
	v_add_co_u32_e32 v72, vcc, 0xc000, v64
	s_mov_b32 s21, 0x18000
	s_nop 0
	v_addc_co_u32_e32 v73, vcc, 0, v65, vcc
	v_add_co_u32_e32 v80, vcc, s21, v64
	v_lshl_add_u64 v[56:57], v[92:93], 0, s[10:11]
	s_nop 0
	v_addc_co_u32_e32 v81, vcc, 0, v65, vcc
	v_add_co_u32_e32 v88, vcc, 0x24000, v64
	v_lshl_add_u64 v[100:101], s[4:5], 1, v[116:117]
	s_nop 0
	v_addc_co_u32_e32 v89, vcc, 0, v65, vcc
	global_load_dwordx4 v[6:9], v[56:57], off
	global_load_dwordx4 v[10:13], v[56:57], off offset:64
	global_load_dwordx4 v[14:17], v[64:65], off
	global_load_dwordx4 v[24:27], v[64:65], off offset:64
	global_load_dwordx4 v[28:31], v[72:73], off
	global_load_dwordx4 v[32:35], v[72:73], off offset:64
	global_load_dwordx4 v[36:39], v[80:81], off
	global_load_dwordx4 v[40:43], v[80:81], off offset:64
	global_load_dwordx4 v[44:47], v[88:89], off
	global_load_dwordx4 v[48:51], v[88:89], off offset:64
	global_load_dwordx4 v[52:55], v[56:57], off offset:128
	s_nop 0
	global_load_dwordx4 v[56:59], v[56:57], off offset:192
	s_nop 0
	global_load_dwordx4 v[60:63], v[64:65], off offset:128
	s_nop 0
	global_load_dwordx4 v[64:67], v[64:65], off offset:192
	s_nop 0
	global_load_dwordx4 v[68:71], v[72:73], off offset:128
	s_nop 0
	global_load_dwordx4 v[72:75], v[72:73], off offset:192
	s_nop 0
	global_load_dwordx4 v[76:79], v[80:81], off offset:128
	s_nop 0
	global_load_dwordx4 v[80:83], v[80:81], off offset:192
	s_nop 0
	global_load_dwordx4 v[84:87], v[88:89], off offset:128
	s_nop 0
	global_load_dwordx4 v[88:91], v[88:89], off offset:192
	s_mov_b32 s22, 0xc000
	v_add_co_u32_e32 v96, vcc, s22, v100
	s_mov_b32 s23, 0x24000
	s_nop 0
	v_addc_co_u32_e32 v97, vcc, 0, v101, vcc
	v_add_co_u32_e32 v102, vcc, s21, v100
	v_lshl_add_u64 v[124:125], s[8:9], 1, v[116:117]
	s_nop 0
	v_addc_co_u32_e32 v103, vcc, 0, v101, vcc
	v_add_co_u32_e32 v104, vcc, s23, v100
	v_lshl_add_u64 v[112:113], s[0:1], 1, v[92:93]
	s_nop 0
	v_addc_co_u32_e32 v105, vcc, 0, v101, vcc
	v_add_co_u32_e32 v120, vcc, s22, v124
	global_load_dwordx4 v[92:95], v[100:101], off
	s_nop 0
	global_load_dwordx4 v[96:99], v[96:97], off
	v_addc_co_u32_e32 v121, vcc, 0, v125, vcc
	v_add_co_u32_e32 v126, vcc, s21, v124
	global_load_dwordx4 v[100:103], v[102:103], off
	s_nop 0
	global_load_dwordx4 v[104:107], v[104:105], off
	s_nop 0
	global_load_dwordx4 v[108:111], v[112:113], off offset:2048
	s_nop 0
	global_load_dwordx4 v[112:115], v[112:113], off offset:2112
	v_addc_co_u32_e32 v127, vcc, 0, v125, vcc
	v_add_co_u32_e32 v128, vcc, s23, v124
	global_load_dwordx4 v[116:119], v[124:125], off
	s_nop 0
	global_load_dwordx4 v[120:123], v[120:121], off
	v_addc_co_u32_e32 v129, vcc, 0, v125, vcc
	global_load_dwordx4 v[124:127], v[126:127], off
	s_nop 0
	global_load_dwordx4 v[128:131], v[128:129], off
	s_waitcnt vmcnt(0)
	v_mfma_f32_16x16x32_bf16 v[14:17], v[14:17], v[6:9], 0
	s_andn2_b64 vcc, exec, s[2:3]
	v_mfma_f32_16x16x32_bf16 v[28:31], v[28:31], v[6:9], 0
	v_mfma_f32_16x16x32_bf16 v[36:39], v[36:39], v[6:9], 0
	v_mfma_f32_16x16x32_bf16 v[6:9], v[44:47], v[6:9], 0
	v_mfma_f32_16x16x32_bf16 v[14:17], v[24:27], v[10:13], v[14:17]
	v_mfma_f32_16x16x32_bf16 v[24:27], v[32:35], v[10:13], v[28:31]
	v_mfma_f32_16x16x32_bf16 v[28:31], v[40:43], v[10:13], v[36:39]
	v_mfma_f32_16x16x32_bf16 v[6:9], v[48:51], v[10:13], v[6:9]
	v_mfma_f32_16x16x32_bf16 v[10:13], v[60:63], v[52:55], v[14:17]
	v_mfma_f32_16x16x32_bf16 v[14:17], v[68:71], v[52:55], v[24:27]
	v_mfma_f32_16x16x32_bf16 v[24:27], v[76:79], v[52:55], v[28:31]
	v_mfma_f32_16x16x32_bf16 v[28:31], v[92:95], v[108:111], 0
	v_mfma_f32_16x16x32_bf16 v[10:13], v[64:67], v[56:59], v[10:13]
	v_mfma_f32_16x16x32_bf16 v[32:35], v[96:99], v[108:111], 0
	v_mfma_f32_16x16x32_bf16 v[36:39], v[100:103], v[108:111], 0
	s_nop 5
	ds_write_b128 v21, v[10:13]
	v_mfma_f32_16x16x32_bf16 v[28:31], v[116:119], v[112:115], v[28:31]
	v_mfma_f32_16x16x32_bf16 v[6:9], v[84:87], v[52:55], v[6:9]
	v_mfma_f32_16x16x32_bf16 v[14:17], v[72:75], v[56:59], v[14:17]
	v_mfma_f32_16x16x32_bf16 v[10:13], v[120:123], v[112:115], v[32:35]
	s_nop 4
	ds_write_b128 v21, v[28:31] offset:32768
	s_nop 0
	ds_write_b128 v21, v[14:17] offset:1024
	ds_write_b128 v21, v[10:13] offset:33792
	v_mfma_f32_16x16x32_bf16 v[24:27], v[80:83], v[56:59], v[24:27]
	v_mfma_f32_16x16x32_bf16 v[40:43], v[104:107], v[108:111], 0
	v_mfma_f32_16x16x32_bf16 v[10:13], v[124:127], v[112:115], v[36:39]
	v_mfma_f32_16x16x32_bf16 v[6:9], v[88:91], v[56:59], v[6:9]
	s_nop 4
	ds_write_b128 v21, v[24:27] offset:2048
	s_nop 0
	ds_write_b128 v21, v[10:13] offset:34816
	ds_write_b128 v21, v[6:9] offset:3072
	v_mfma_f32_16x16x32_bf16 v[6:9], v[128:131], v[112:115], v[40:43]
	s_nop 7
	ds_write_b128 v21, v[6:9] offset:35840
	s_waitcnt lgkmcnt(0)
	s_barrier
	s_cbranch_vccnz .LBB0_771
	ds_read_b128 v[6:9], v19
	ds_read_b128 v[10:13], v19 offset:32768
	ds_read_b128 v[14:17], v19 offset:4096
	ds_read_b128 v[32:35], v19 offset:36864
	ds_read_b128 v[36:39], v19 offset:8192
	ds_read_b128 v[40:43], v19 offset:40960
	ds_read_b128 v[44:47], v19 offset:12288
	ds_read_b128 v[48:51], v19 offset:45056
	ds_read_b128 v[52:55], v19 offset:16384
	ds_read_b128 v[56:59], v19 offset:49152
	ds_read_b128 v[60:63], v19 offset:20480
	ds_read_b128 v[64:67], v19 offset:53248
	ds_read_b128 v[68:71], v19 offset:24576
	ds_read_b128 v[72:75], v19 offset:57344
	ds_read_b128 v[76:79], v19 offset:28672
	ds_read_b128 v[80:83], v19 offset:61440
	v_lshlrev_b32_e32 v2, 11, v2
	v_lshl_add_u64 v[30:31], s[68:69], 0, v[2:3]
	v_add_u32_e32 v96, s20, v20
	v_ashrrev_i32_e32 v97, 31, v96
	v_lshlrev_b64 v[96:97], 1, v[96:97]
	v_lshl_add_u64 v[98:99], s[36:37], 0, v[2:3]
	v_lshl_add_u64 v[98:99], v[98:99], 0, v[96:97]
	global_load_dwordx2 v[102:103], v[98:99], off
	v_readlane_b32 vcc_lo, v252, 60
	v_readlane_b32 vcc_hi, v252, 61
	s_nop 1
	v_lshl_add_u64 v[100:101], vcc, 0, v[2:3]
	v_lshl_add_u64 v[100:101], v[100:101], 0, v[96:97]
	global_load_dwordx2 v[104:105], v[100:101], off
	s_waitcnt lgkmcnt(13)
	v_pk_add_f32 v[16:17], v[8:9], v[16:17]
	v_pk_add_f32 v[14:15], v[6:7], v[14:15]
	s_waitcnt lgkmcnt(12)
	v_pk_add_f32 v[12:13], v[12:13], v[34:35]
	v_pk_add_f32 v[10:11], v[10:11], v[32:33]
	s_waitcnt lgkmcnt(11)
	v_pk_add_f32 v[16:17], v[16:17], v[38:39]
	v_pk_add_f32 v[14:15], v[14:15], v[36:37]
	s_waitcnt lgkmcnt(10)
	v_pk_add_f32 v[12:13], v[12:13], v[42:43]
	v_pk_add_f32 v[10:11], v[10:11], v[40:41]
	s_waitcnt lgkmcnt(9)
	v_pk_add_f32 v[16:17], v[16:17], v[46:47]
	v_pk_add_f32 v[14:15], v[14:15], v[44:45]
	s_waitcnt lgkmcnt(8)
	v_pk_add_f32 v[12:13], v[12:13], v[50:51]
	v_pk_add_f32 v[10:11], v[10:11], v[48:49]
	s_waitcnt lgkmcnt(7)
	v_pk_add_f32 v[16:17], v[16:17], v[54:55]
	v_pk_add_f32 v[14:15], v[14:15], v[52:53]
	s_waitcnt lgkmcnt(6)
	v_pk_add_f32 v[12:13], v[12:13], v[58:59]
	v_pk_add_f32 v[10:11], v[10:11], v[56:57]
	s_waitcnt lgkmcnt(5)
	v_pk_add_f32 v[16:17], v[16:17], v[62:63]
	v_pk_add_f32 v[14:15], v[14:15], v[60:61]
	s_waitcnt lgkmcnt(4)
	v_pk_add_f32 v[12:13], v[12:13], v[66:67]
	v_pk_add_f32 v[10:11], v[10:11], v[64:65]
	s_waitcnt lgkmcnt(3)
	v_pk_add_f32 v[16:17], v[16:17], v[70:71]
	v_pk_add_f32 v[14:15], v[14:15], v[68:69]
	s_waitcnt lgkmcnt(2)
	v_pk_add_f32 v[24:25], v[12:13], v[74:75]
	v_pk_add_f32 v[26:27], v[10:11], v[72:73]
	s_waitcnt lgkmcnt(1)
	v_pk_add_f32 v[6:7], v[14:15], v[76:77]
	v_pk_add_f32 v[8:9], v[16:17], v[78:79]
	v_lshl_add_u64 v[16:17], s[36:37], 0, v[2:3]
	s_waitcnt lgkmcnt(0)
	v_pk_add_f32 v[10:11], v[24:25], v[82:83]
	v_add_u32_e32 v14, s20, v20
	v_readlane_b32 s20, v252, 60
	v_ashrrev_i32_e32 v15, 31, v14
	v_readlane_b32 s21, v252, 61
	v_pk_add_f32 v[12:13], v[26:27], v[80:81]
	v_lshlrev_b64 v[24:25], 1, v[14:15]
	v_lshl_add_u64 v[26:27], s[20:21], 0, v[2:3]
	v_lshl_add_u64 v[14:15], v[16:17], 0, v[24:25]
	v_lshl_add_u64 v[26:27], v[26:27], 0, v[24:25]
	v_lshl_add_u64 v[24:25], v[30:31], 0, v[24:25]
	s_waitcnt vmcnt(1)
	v_lshlrev_b32_e32 v14, 16, v102
	v_and_b32_e32 v15, 0xffff0000, v102
	s_waitcnt vmcnt(0)
	v_lshlrev_b32_e32 v28, 16, v104
	v_and_b32_e32 v29, 0xffff0000, v104
	v_lshlrev_b32_e32 v26, 16, v105
	v_and_b32_e32 v27, 0xffff0000, v105
	v_lshlrev_b32_e32 v16, 16, v103
	v_and_b32_e32 v17, 0xffff0000, v103
	v_pk_mul_f32 v[12:13], v[12:13], v[28:29]
	v_pk_mul_f32 v[10:11], v[10:11], v[26:27]
	v_pk_fma_f32 v[6:7], v[6:7], v[14:15], v[12:13]
	v_pk_fma_f32 v[8:9], v[8:9], v[16:17], v[10:11]
	v_cvt_pk_bf16_f32 v6, v6, v7
	v_cvt_pk_bf16_f32 v7, v8, v9
	global_store_dwordx2 v[24:25], v[6:7], off
	s_branch .LBB0_771
